# prep loop: L2 software prefetch of row t+3 (one full iteration ahead of its real load), on top of v28
# baseline (speedup 1.0000x reference)
.LBB0_873:
	v_mov_b64_e32 v[100:101], v[104:105]
	v_mov_b64_e32 v[102:103], v[106:107]
	v_mov_b64_e32 v[104:105], v[112:113]
	v_mov_b64_e32 v[106:107], v[114:115]
	v_mov_b64_e32 v[112:113], v[132:133]
	v_mov_b64_e32 v[114:115], v[134:135]
	v_mov_b64_e32 v[132:133], v[144:145]
	s_add_i32 s100, s5, 3
	v_readlane_b32 s101, v253, 16
	s_add_i32 s101, s101, -1
	s_min_u32 s100, s100, s101
	v_add_u32_e32 v236, s100, v148
	v_mov_b32_e32 v237, 0
	v_mul_u32_u24_e32 v238, 48, v224
	v_lshlrev_b64 v[236:237], 12, v[236:237]
	v_mov_b32_e32 v239, 0
	v_lshl_add_u64 v[236:237], v[2:3], 0, v[236:237]
	v_lshl_add_u64 v[236:237], v[236:237], 0, v[238:239]
	global_load_dword v240, v[236:237], off
	s_waitcnt vmcnt(5)
	v_mov_b64_e32 v[108:109], v[116:117]
	s_and_b64 vcc, exec, s[8:9]
	v_mov_b64_e32 v[134:135], v[146:147]
	v_mov_b64_e32 v[212:213], v[196:197]
	v_mov_b64_e32 v[208:209], v[192:193]
	v_mov_b64_e32 v[204:205], v[188:189]
	v_mov_b64_e32 v[200:201], v[184:185]
	v_mov_b64_e32 v[214:215], v[198:199]
	v_mov_b64_e32 v[210:211], v[194:195]
	v_mov_b64_e32 v[206:207], v[190:191]
	v_mov_b64_e32 v[202:203], v[186:187]
	s_mov_b32 s5, s4
	v_mov_b64_e32 v[110:111], v[118:119]
	v_mov_b32_e32 v144, v128
	v_mov_b32_e32 v145, v129
	v_mov_b32_e32 v146, v130
	v_mov_b32_e32 v147, v131
	v_mov_b32_e32 v140, v124
	v_mov_b32_e32 v141, v125
	v_mov_b32_e32 v142, v126
	v_mov_b32_e32 v143, v127
	v_mov_b32_e32 v136, v120
	v_mov_b32_e32 v137, v121
	v_mov_b32_e32 v138, v122
	v_mov_b32_e32 v139, v123
	v_mov_b32_e32 v216, v116
	v_mov_b32_e32 v217, v117
	v_mov_b32_e32 v218, v118
	v_mov_b32_e32 v219, v119
	s_cbranch_vccnz .LBB0_895
